# v44 + MLA half 2: first four V-fragment reads of P.V issued before the last QK MFMA pair into dead v[206:213]
# speedup vs baseline: 1.0060x; 1.0060x over previous
.Lattn_mla_nopf:
	s_waitcnt lgkmcnt(0)
	v_mfma_f32_32x32x16_bf16 v[82:97], v[146:149], v[134:137], v[82:97]
	v_mfma_f32_32x32x16_bf16 v[66:81], v[150:153], v[134:137], v[66:81]
	ds_read_b128 v[146:149], v180 offset:32768
	ds_read_b128 v[150:153], v180 offset:40960
	v_exp_f32_e32 v231, v231
	v_exp_f32_e32 v234, v234
	v_exp_f32_e32 v235, v235
	v_add_f32_e32 v245, v231, v245
	v_add_f32_e32 v245, v234, v245
	v_add_f32_e32 v245, v235, v245
	s_waitcnt lgkmcnt(0)
	v_mfma_f32_32x32x16_bf16 v[82:97], v[146:149], v[130:133], v[82:97]
	v_mfma_f32_32x32x16_bf16 v[66:81], v[150:153], v[130:133], v[66:81]
	ds_read_b128 v[146:149], v182 offset:32768
	ds_read_b128 v[150:153], v182 offset:40960
	v_exp_f32_e32 v236, v236
	v_exp_f32_e32 v237, v237
	v_exp_f32_e32 v238, v238
	v_add_f32_e32 v245, v236, v245
	v_add_f32_e32 v245, v237, v245
	v_add_f32_e32 v245, v238, v245
	s_waitcnt lgkmcnt(0)
	v_mfma_f32_32x32x16_bf16 v[82:97], v[146:149], v[126:129], v[82:97]
	v_mfma_f32_32x32x16_bf16 v[66:81], v[150:153], v[126:129], v[66:81]
	ds_read_b128 v[146:149], v186 offset:32768
	ds_read_b128 v[150:153], v186 offset:40960
	v_exp_f32_e32 v239, v239
	v_exp_f32_e32 v240, v240
	v_exp_f32_e32 v241, v241
	v_add_f32_e32 v245, v239, v245
	v_add_f32_e32 v245, v240, v245
	v_add_f32_e32 v245, v241, v245
	s_waitcnt lgkmcnt(0)
	v_mfma_f32_32x32x16_bf16 v[82:97], v[146:149], v[122:125], v[82:97]
	v_mfma_f32_32x32x16_bf16 v[66:81], v[150:153], v[122:125], v[66:81]
	ds_read_b128 v[146:149], v188 offset:32768
	ds_read_b128 v[150:153], v188 offset:40960
	v_exp_f32_e32 v155, v155
	v_exp_f32_e32 v156, v156
	v_exp_f32_e32 v157, v157
	v_add_f32_e32 v245, v155, v245
	v_add_f32_e32 v245, v156, v245
	v_add_f32_e32 v245, v157, v245
	s_waitcnt lgkmcnt(0)
	v_mfma_f32_32x32x16_bf16 v[82:97], v[146:149], v[118:121], v[82:97]
	v_mfma_f32_32x32x16_bf16 v[66:81], v[150:153], v[118:121], v[66:81]
	ds_read_b128 v[146:149], v190 offset:32768
	ds_read_b128 v[150:153], v190 offset:40960
	v_exp_f32_e32 v202, v202
	v_exp_f32_e32 v215, v215
	v_exp_f32_e32 v216, v216
	v_add_f32_e32 v245, v202, v245
	v_add_f32_e32 v245, v215, v245
	v_add_f32_e32 v245, v216, v245
	s_waitcnt lgkmcnt(0)
	v_mfma_f32_32x32x16_bf16 v[82:97], v[146:149], v[114:117], v[82:97]
	v_mfma_f32_32x32x16_bf16 v[66:81], v[150:153], v[114:117], v[66:81]
	ds_read_b128 v[146:149], v192
	ds_read_b128 v[150:153], v192 offset:4096
	v_exp_f32_e32 v217, v217
	v_exp_f32_e32 v218, v218
	v_exp_f32_e32 v219, v219
	v_add_f32_e32 v245, v217, v245
	v_add_f32_e32 v245, v218, v245
	v_add_f32_e32 v245, v219, v245
	s_waitcnt lgkmcnt(0)
	v_mfma_f32_32x32x16_bf16 v[82:97], v[146:149], v[110:113], v[82:97]
	v_mfma_f32_32x32x16_bf16 v[66:81], v[150:153], v[110:113], v[66:81]
	ds_read_b128 v[146:149], v194
	ds_read_b128 v[150:153], v194 offset:4096
	v_exp_f32_e32 v220, v220
	v_exp_f32_e32 v221, v221
	v_exp_f32_e32 v222, v222
	v_add_f32_e32 v245, v220, v245
	v_add_f32_e32 v245, v221, v245
	v_add_f32_e32 v245, v222, v245
	s_waitcnt lgkmcnt(0)
	v_mfma_f32_32x32x16_bf16 v[82:97], v[146:149], v[106:109], v[82:97]
	v_mfma_f32_32x32x16_bf16 v[66:81], v[150:153], v[106:109], v[66:81]
	ds_read_b128 v[146:149], v196
	ds_read_b128 v[150:153], v196 offset:4096
	v_exp_f32_e32 v223, v223
	v_exp_f32_e32 v242, v232
	v_exp_f32_e32 v243, v233
	v_add_f32_e32 v245, v223, v245
	v_add_f32_e32 v245, v242, v245
	v_add_f32_e32 v245, v243, v245
	s_waitcnt lgkmcnt(0)
	v_mfma_f32_32x32x16_bf16 v[82:97], v[146:149], v[102:105], v[82:97]
	v_mfma_f32_32x32x16_bf16 v[66:81], v[150:153], v[102:105], v[66:81]
	ds_read_b128 v[146:149], v199
	ds_read_b128 v[150:153], v199 offset:4096
	v_lshl_add_u32 v214, s23, 14, v200
	ds_read_b64_tr_b16 v[206:207], v214 offset:0
	ds_read_b64_tr_b16 v[208:209], v214 offset:0x800
	ds_read_b64_tr_b16 v[210:211], v214 offset:0x1000
	ds_read_b64_tr_b16 v[212:213], v214 offset:0x1800
	v_exp_f32_e32 v244, v154
	s_waitcnt lgkmcnt(4)
	v_mfma_f32_32x32x16_bf16 v[82:97], v[146:149], v[98:101], v[82:97]
	v_mfma_f32_32x32x16_bf16 v[66:81], v[150:153], v[98:101], v[66:81]
	v_add_f32_e32 v232, v244, v245
	v_mov_b32_e32 v233, v232
	s_nop 1
	v_permlane32_swap_b32_e32 v232, v233
	v_cvt_pk_bf16_f32 v146, v224, v225
	v_cvt_pk_bf16_f32 v147, v226, v227
	v_cvt_pk_bf16_f32 v148, v228, v229
	v_cvt_pk_bf16_f32 v149, v230, v231
	v_cvt_pk_bf16_f32 v150, v234, v235
	v_cvt_pk_bf16_f32 v151, v236, v237
	v_cvt_pk_bf16_f32 v152, v238, v239
	v_cvt_pk_bf16_f32 v153, v240, v241
	v_cvt_pk_bf16_f32 v154, v155, v156
	v_cvt_pk_bf16_f32 v155, v157, v202
	v_cvt_pk_bf16_f32 v156, v215, v216
	v_cvt_pk_bf16_f32 v157, v217, v218
	v_cvt_pk_bf16_f32 v216, v219, v220
	v_cvt_pk_bf16_f32 v217, v221, v222
	v_cvt_pk_bf16_f32 v218, v223, v242
	v_cvt_pk_bf16_f32 v219, v243, v244
	s_nop 0
	v_permlane32_swap_b32_e32 v146, v148
	v_permlane32_swap_b32_e32 v147, v149
	v_permlane32_swap_b32_e32 v150, v152
	v_permlane32_swap_b32_e32 v151, v153
	v_permlane32_swap_b32_e32 v154, v156
	v_permlane32_swap_b32_e32 v155, v157
	v_permlane32_swap_b32_e32 v216, v218
	v_permlane32_swap_b32_e32 v217, v219
	ds_read_b64_tr_b16 v[228:229], v214 offset:0x2000
	ds_read_b64_tr_b16 v[230:231], v214 offset:0x2800
	ds_read_b64_tr_b16 v[234:235], v214 offset:0x3000
	ds_read_b64_tr_b16 v[236:237], v214 offset:0x3800
	s_nop 0
	s_waitcnt lgkmcnt(6)
	v_mfma_f32_32x32x16_bf16 v[2:17], v[146:149], v[206:209], v[2:17]
	ds_read_b64_tr_b16 v[220:221], v214 offset:0x200
	ds_read_b64_tr_b16 v[222:223], v214 offset:0xa00
	v_max_f32_e32 v202, v83, v83
	v_max_f32_e32 v215, v82, v82
	v_max_f32_e32 v202, v215, v202
	v_max3_f32 v202, v202, v84, v85
	v_max3_f32 v202, v202, v86, v87
	s_waitcnt lgkmcnt(6)
	v_mfma_f32_32x32x16_bf16 v[2:17], v[150:153], v[210:213], v[2:17]
	ds_read_b64_tr_b16 v[224:225], v214 offset:0x1200
	ds_read_b64_tr_b16 v[226:227], v214 offset:0x1a00
	v_max3_f32 v202, v202, v88, v89
	v_max3_f32 v202, v202, v90, v91
	v_max3_f32 v202, v202, v92, v93
	v_max3_f32 v202, v202, v94, v95
	v_max3_f32 v202, v202, v96, v97
	s_waitcnt lgkmcnt(6)
	v_mfma_f32_32x32x16_bf16 v[2:17], v[154:157], v[228:231], v[2:17]
	ds_read_b64_tr_b16 v[228:229], v214 offset:0x2200
	ds_read_b64_tr_b16 v[230:231], v214 offset:0x2a00
	ds_read_b64_tr_b16 v[238:239], v214 offset:0x3200
	ds_read_b64_tr_b16 v[240:241], v214 offset:0x3a00
	s_waitcnt lgkmcnt(8)
	v_mfma_f32_32x32x16_bf16 v[2:17], v[216:219], v[234:237], v[2:17]
	s_waitcnt lgkmcnt(6)
	v_mfma_f32_32x32x16_bf16 v[50:65], v[146:149], v[220:223], v[50:65]
	v_max3_f32 v202, v202, v66, v67
	v_max3_f32 v202, v202, v68, v69
	v_max3_f32 v202, v202, v70, v71
	v_max3_f32 v202, v202, v72, v73
	v_max3_f32 v202, v202, v74, v75
	v_max3_f32 v202, v202, v76, v77
	v_max3_f32 v202, v202, v78, v79
	s_waitcnt lgkmcnt(4)
	v_mfma_f32_32x32x16_bf16 v[50:65], v[150:153], v[224:227], v[50:65]
	v_max3_f32 v202, v202, v80, v81
	v_mov_b32_e32 v215, v202
	s_nop 1
	v_permlane32_swap_b32_e32 v202, v215
	v_max_f32_e32 v215, v215, v215
	v_max_f32_e32 v202, v202, v202
	v_max_f32_e32 v202, v202, v215
	v_max_f32_e32 v220, v165, v165
	v_sub_f32_e32 v215, v202, v165
	v_max_f32_e32 v202, v220, v202
	v_sub_f32_e32 v220, v165, v202
	v_mul_f32_e32 v220, 0x3dd53b94, v220
	s_waitcnt lgkmcnt(2)
	v_mfma_f32_32x32x16_bf16 v[50:65], v[154:157], v[228:231], v[50:65]
	v_exp_f32_e32 v220, v220
	v_cmp_ge_f32_e32 vcc, s77, v215
	s_cmp_eq_u64 vcc, exec
	s_cselect_b64 s[4:5], -1, 0
	v_cndmask_b32_e64 v215, v220, 1.0, s[4:5]
	ds_read_b64_tr_b16 v[220:221], v214 offset:0x400
	ds_read_b64_tr_b16 v[222:223], v214 offset:0xc00
	ds_read_b64_tr_b16 v[224:225], v214 offset:0x1400
	s_waitcnt lgkmcnt(3)
	v_mfma_f32_32x32x16_bf16 v[50:65], v[216:219], v[238:241], v[50:65]
	ds_read_b64_tr_b16 v[226:227], v214 offset:0x1c00
	ds_read_b64_tr_b16 v[228:229], v214 offset:0x2400
	ds_read_b64_tr_b16 v[230:231], v214 offset:0x2c00
	ds_read_b64_tr_b16 v[234:235], v214 offset:0x3400
	ds_read_b64_tr_b16 v[236:237], v214 offset:0x3c00
	s_waitcnt lgkmcnt(6)
	v_mfma_f32_32x32x16_bf16 v[34:49], v[146:149], v[220:223], v[34:49]
	ds_read_b64_tr_b16 v[220:221], v214 offset:0x600
	ds_read_b64_tr_b16 v[222:223], v214 offset:0xe00
	s_waitcnt lgkmcnt(6)
	v_mfma_f32_32x32x16_bf16 v[34:49], v[150:153], v[224:227], v[34:49]
	ds_read_b64_tr_b16 v[224:225], v214 offset:0x1600
	ds_read_b64_tr_b16 v[226:227], v214 offset:0x1e00
	s_waitcnt lgkmcnt(6)
	v_mfma_f32_32x32x16_bf16 v[34:49], v[154:157], v[228:231], v[34:49]
	ds_read_b64_tr_b16 v[228:229], v214 offset:0x2600
	ds_read_b64_tr_b16 v[230:231], v214 offset:0x2e00
	ds_read_b64_tr_b16 v[238:239], v214 offset:0x3600
	ds_read_b64_tr_b16 v[240:241], v214 offset:0x3e00
	s_waitcnt lgkmcnt(8)
	v_mfma_f32_32x32x16_bf16 v[34:49], v[216:219], v[234:237], v[34:49]
	s_waitcnt lgkmcnt(6)
	v_mfma_f32_32x32x16_bf16 v[18:33], v[146:149], v[220:223], v[18:33]
	v_cmp_gt_f32_e32 vcc, 1.0, v215
	s_waitcnt lgkmcnt(4)
	v_mfma_f32_32x32x16_bf16 v[18:33], v[150:153], v[224:227], v[18:33]
	s_waitcnt lgkmcnt(2)
	v_mfma_f32_32x32x16_bf16 v[18:33], v[154:157], v[228:231], v[18:33]
	s_waitcnt lgkmcnt(0)
	v_mfma_f32_32x32x16_bf16 v[18:33], v[216:219], v[238:241], v[18:33]
	s_cbranch_vccz .LBB0_553
	s_and_saveexec_b64 s[0:1], s[2:3]
	ds_write_b32 v170, v215 offset:128
	s_or_b64 exec, exec, s[0:1]
	s_waitcnt lgkmcnt(0)
	ds_read_b128 v[146:149], v158 offset:224
	ds_read_b128 v[150:153], v158 offset:192
	ds_read_b128 v[154:157], v158 offset:160
	ds_read_b128 v[216:219], v158 offset:128
	s_waitcnt lgkmcnt(0)
	v_pk_mul_f32 v[16:17], v[16:17], v[148:149]
	v_pk_mul_f32 v[12:13], v[12:13], v[152:153]
	v_pk_mul_f32 v[8:9], v[8:9], v[156:157]
	v_pk_mul_f32 v[4:5], v[4:5], v[218:219]
	v_pk_mul_f32 v[14:15], v[14:15], v[146:147]
	v_pk_mul_f32 v[10:11], v[10:11], v[150:151]
	v_pk_mul_f32 v[6:7], v[6:7], v[154:155]
	v_pk_mul_f32 v[2:3], v[2:3], v[216:217]
	v_pk_mul_f32 v[64:65], v[64:65], v[148:149]
	v_pk_mul_f32 v[60:61], v[60:61], v[152:153]
	v_pk_mul_f32 v[56:57], v[56:57], v[156:157]
	v_pk_mul_f32 v[52:53], v[52:53], v[218:219]
	v_pk_mul_f32 v[62:63], v[62:63], v[146:147]
	v_pk_mul_f32 v[58:59], v[58:59], v[150:151]
	v_pk_mul_f32 v[54:55], v[54:55], v[154:155]
	v_pk_mul_f32 v[50:51], v[50:51], v[216:217]
	v_pk_mul_f32 v[48:49], v[48:49], v[148:149]
	v_pk_mul_f32 v[44:45], v[44:45], v[152:153]
	v_pk_mul_f32 v[40:41], v[40:41], v[156:157]
	v_pk_mul_f32 v[36:37], v[36:37], v[218:219]
	v_pk_mul_f32 v[46:47], v[46:47], v[146:147]
	v_pk_mul_f32 v[42:43], v[42:43], v[150:151]
	v_pk_mul_f32 v[38:39], v[38:39], v[154:155]
	v_pk_mul_f32 v[34:35], v[34:35], v[216:217]
	v_pk_mul_f32 v[32:33], v[32:33], v[148:149]
	v_pk_mul_f32 v[28:29], v[28:29], v[152:153]
	v_pk_mul_f32 v[24:25], v[24:25], v[156:157]
	v_pk_mul_f32 v[20:21], v[20:21], v[218:219]
	v_pk_mul_f32 v[30:31], v[30:31], v[146:147]
	v_pk_mul_f32 v[26:27], v[26:27], v[150:151]
	v_pk_mul_f32 v[22:23], v[22:23], v[154:155]
	v_pk_mul_f32 v[18:19], v[18:19], v[216:217]
